# v_combo8 + p6a_prep: next unit's 26 input loads requested one unit ahead (register-renamed clone of the address/load block), counted waits removed
# baseline (speedup 1.0000x reference)
.LBB0_548:
	s_cmp_lt_i32 s60, 7
	s_cselect_b64 s[0:1], -1, 0
	s_cmp_gt_i32 s61, 6
	s_cselect_b64 s[2:3], -1, 0
	s_and_b64 s[0:1], s[0:1], s[2:3]
	s_andn2_b64 vcc, exec, s[0:1]
	s_cbranch_vccnz .LBB0_606
	s_cmpk_gt_i32 s72, 0xfff
	s_cbranch_scc1 .LBB0_554
	v_readlane_b32 s42, v247, 0
	v_readlane_b32 s43, v247, 1
	s_add_u32 s34, s42, 0x8000000
	s_addc_u32 s35, s43, 0
	s_add_u32 s36, s42, 0xc000000
	s_addc_u32 s37, s43, 0
	v_lshlrev_b32_e32 v0, 1, v170
	s_add_u32 s38, s42, 0x10000000
	v_and_b32_e32 v20, 0x7e, v0
	s_addc_u32 s39, s43, 0
	v_lshlrev_b32_e32 v22, 2, v20
	s_add_u32 s40, s42, 0x14000000
	v_lshrrev_b32_e32 v0, 6, v170
	v_add_u32_e32 v21, 0, v22
	v_mov_b32_e32 v23, 0
	s_addc_u32 s41, s43, 0
	v_lshlrev_b32_e32 v94, 13, v0
	v_lshl_add_u32 v95, v0, 9, v21
	s_movk_i32 s2, 0x7f
	s_movk_i32 s4, 0xbf
	s_movk_i32 s6, 0x80
	s_movk_i32 s8, 0xff
	s_movk_i32 s10, 0xc0
	s_movk_i32 s12, 0x13f
	s_movk_i32 s14, 0x100
	s_movk_i32 s16, 0x17f
	s_movk_i32 s18, 0x140
	s_movk_i32 s20, 0x1bf
	s_movk_i32 s22, 0x180
	s_movk_i32 s24, 0x1ff
	s_movk_i32 s26, 0x1c0
	v_lshl_add_u64 v[0:1], s[42:43], 0, v[22:23]
	s_mov_b64 s[42:43], 0x2200000
	v_cmp_gt_u32_e64 s[0:1], 64, v170
	v_cmp_lt_u32_e64 s[2:3], s2, v170
	v_cmp_lt_u32_e64 s[4:5], s4, v170
	v_cmp_gt_u32_e64 s[6:7], s6, v170
	v_cmp_lt_u32_e64 s[8:9], s8, v170
	v_cmp_gt_u32_e64 s[10:11], s10, v170
	v_cmp_lt_u32_e64 s[12:13], s12, v170
	v_cmp_gt_u32_e64 s[14:15], s14, v170
	v_cmp_lt_u32_e64 s[16:17], s16, v170
	v_cmp_gt_u32_e64 s[18:19], s18, v170
	v_cmp_lt_u32_e64 s[20:21], s20, v170
	v_cmp_gt_u32_e64 s[22:23], s22, v170
	v_cmp_lt_u32_e64 s[24:25], s24, v170
	v_cmp_gt_u32_e64 s[26:27], s26, v170
	v_lshl_add_u64 v[24:25], v[0:1], 0, s[42:43]
	s_movk_i32 s33, 0x1000
	s_movk_i32 s46, 0x2000
	s_movk_i32 s47, 0x3000
	v_mov_b32_e32 v96, 0x600
	s_mov_b32 s48, s72
	s_mov_b32 s69, s48
	v_mov_b32_e32 v146, v20
	v_mov_b32_e32 v149, v23
	s_bfe_u32 s67, s69, 0x30007
	s_lshl_b32 s68, s67, 7
	v_readlane_b32 s76, v247, 26
	v_or_b32_e32 v126, s68, v146
	v_readlane_b32 s82, v247, 32
	v_readlane_b32 s83, v247, 33
	v_lshlrev_b32_e32 v148, 2, v126
	s_mov_b64 s[54:55], s[82:83]
	v_lshl_add_u64 v[126:127], s[54:55], 0, v[148:149]
	s_ashr_i32 s62, s69, 10
	v_add_co_u32_e32 v126, vcc, 0x1000, v126
	s_and_b32 s66, s69, 0x7f
	s_nop 0
	v_addc_co_u32_e32 v127, vcc, 0, v127, vcc
	s_ashr_i32 s63, s62, 31
	global_load_dwordx2 v[126:127], v[126:127], off
	s_nop 0
	global_load_dwordx2 v[128:129], v148, s[82:83]
	s_lshl_b64 s[64:65], s[62:63], 23
	v_lshl_add_u32 v148, s66, 16, v94
	v_lshl_add_u64 v[130:131], s[64:65], 0, v[148:149]
	v_or_b32_e32 v130, s68, v130
	v_or_b32_e32 v130, v130, v146
	v_lshlrev_b64 v[152:153], 1, v[130:131]
	v_lshl_add_u64 v[160:161], s[34:35], 0, v[152:153]
	v_add_co_u32_e32 v130, vcc, s33, v160
	v_lshl_add_u64 v[158:159], s[36:37], 0, v[152:153]
	s_nop 0
	v_addc_co_u32_e32 v131, vcc, 0, v161, vcc
	v_add_co_u32_e32 v132, vcc, s33, v158
	v_lshl_add_u64 v[156:157], s[38:39], 0, v[152:153]
	s_nop 0
	v_addc_co_u32_e32 v133, vcc, 0, v159, vcc
	global_load_dword v142, v[158:159], off
	global_load_dword v172, v[156:157], off offset:2048
	global_load_dword v181, v[130:131], off offset:2048
	global_load_dword v143, v[132:133], off offset:2048
	global_load_dword v144, v[158:159], off offset:2048
	v_add_co_u32_e32 v130, vcc, s46, v158
	v_readlane_b32 s77, v247, 27
	s_nop 0
	v_addc_co_u32_e32 v131, vcc, 0, v159, vcc
	v_add_co_u32_e32 v132, vcc, s46, v160
	global_load_dword v145, v[130:131], off offset:-4096
	global_load_dword v154, v[130:131], off
	v_addc_co_u32_e32 v133, vcc, 0, v161, vcc
	v_add_co_u32_e32 v134, vcc, s33, v156
	v_readlane_b32 s78, v247, 28
	s_nop 0
	v_addc_co_u32_e32 v135, vcc, 0, v157, vcc
	v_add_co_u32_e32 v136, vcc, s46, v156
	v_readlane_b32 s79, v247, 29
	s_nop 0
	v_addc_co_u32_e32 v137, vcc, 0, v157, vcc
	global_load_dword v173, v[136:137], off
	global_load_dword v174, v[136:137], off offset:2048
	global_load_dword v155, v[130:131], off offset:2048
	v_add_co_u32_e32 v130, vcc, s47, v160
	v_readlane_b32 s80, v247, 30
	s_nop 0
	v_addc_co_u32_e32 v131, vcc, 0, v161, vcc
	v_add_co_u32_e32 v138, vcc, s47, v158
	v_readlane_b32 s81, v247, 31
	s_nop 0
	v_addc_co_u32_e32 v139, vcc, 0, v159, vcc
	global_load_dword v162, v[138:139], off
	v_add_co_u32_e32 v140, vcc, s47, v156
	v_readlane_b32 s84, v247, 34
	s_nop 0
	v_addc_co_u32_e32 v141, vcc, 0, v157, vcc
	global_load_dword v175, v[156:157], off
	global_load_dword v184, v[160:161], off
	global_load_dword v185, v[160:161], off offset:2048
	global_load_dword v163, v[140:141], off offset:2048
	global_load_dword v164, v[138:139], off offset:2048
	global_load_dword v176, v[136:137], off offset:-4096
	global_load_dword v182, v[132:133], off
	global_load_dword v180, v[132:133], off offset:2048
	global_load_dword v177, v[140:141], off
	global_load_dword v183, v[132:133], off offset:-4096
	global_load_dword v178, v[134:135], off offset:2048
	global_load_dword v179, v[130:131], off
	global_load_dword v148, v[130:131], off offset:2048
	s_waitcnt vmcnt(0)
	s_branch .LBB0_552

.LBB0_552:
	s_waitcnt vmcnt(32)
	s_bfe_u32 s50, s48, 0x30007
	s_lshl_b32 s51, s50, 7
	v_readlane_b32 s76, v247, 26
	v_or_b32_e32 v0, s51, v20
	v_readlane_b32 s82, v247, 32
	v_readlane_b32 s83, v247, 33
	v_lshlrev_b32_e32 v22, 2, v0
	s_mov_b64 s[54:55], s[82:83]
	v_lshl_add_u64 v[0:1], s[54:55], 0, v[22:23]
	s_ashr_i32 s42, s48, 10
	v_add_co_u32_e32 v0, vcc, 0x1000, v0
	s_and_b32 s49, s48, 0x7f
	s_nop 0
	v_addc_co_u32_e32 v1, vcc, 0, v1, vcc
	s_ashr_i32 s43, s42, 31
	v_mov_b32_e32 v0, v126
	v_mov_b32_e32 v1, v127
	s_nop 0
	v_mov_b32_e32 v2, v128
	v_mov_b32_e32 v3, v129
	s_lshl_b64 s[44:45], s[42:43], 23
	v_lshl_add_u32 v22, s49, 16, v94
	v_lshl_add_u64 v[4:5], s[44:45], 0, v[22:23]
	v_or_b32_e32 v4, s51, v4
	v_or_b32_e32 v4, v4, v20
	v_lshlrev_b64 v[26:27], 1, v[4:5]
	v_lshl_add_u64 v[34:35], s[34:35], 0, v[26:27]
	v_add_co_u32_e32 v4, vcc, s33, v34
	v_lshl_add_u64 v[32:33], s[36:37], 0, v[26:27]
	s_nop 0
	v_addc_co_u32_e32 v5, vcc, 0, v35, vcc
	v_add_co_u32_e32 v6, vcc, s33, v32
	v_lshl_add_u64 v[30:31], s[38:39], 0, v[26:27]
	s_nop 0
	v_addc_co_u32_e32 v7, vcc, 0, v33, vcc
	v_mov_b32_e32 v16, v142
	v_mov_b32_e32 v46, v172
	v_mov_b32_e32 v99, v181
	v_mov_b32_e32 v17, v143
	v_mov_b32_e32 v18, v144
	v_add_co_u32_e32 v4, vcc, s46, v32
	v_readlane_b32 s77, v247, 27
	s_nop 0
	v_addc_co_u32_e32 v5, vcc, 0, v33, vcc
	v_add_co_u32_e32 v6, vcc, s46, v34
	v_mov_b32_e32 v19, v145
	v_mov_b32_e32 v28, v154
	v_addc_co_u32_e32 v7, vcc, 0, v35, vcc
	v_add_co_u32_e32 v8, vcc, s33, v30
	v_readlane_b32 s78, v247, 28
	s_nop 0
	v_addc_co_u32_e32 v9, vcc, 0, v31, vcc
	v_add_co_u32_e32 v10, vcc, s46, v30
	v_readlane_b32 s79, v247, 29
	s_nop 0
	v_addc_co_u32_e32 v11, vcc, 0, v31, vcc
	v_mov_b32_e32 v47, v173
	v_mov_b32_e32 v52, v174
	v_mov_b32_e32 v29, v155
	v_add_co_u32_e32 v4, vcc, s47, v34
	v_readlane_b32 s80, v247, 30
	s_nop 0
	v_addc_co_u32_e32 v5, vcc, 0, v35, vcc
	v_add_co_u32_e32 v12, vcc, s47, v32
	v_readlane_b32 s81, v247, 31
	s_nop 0
	v_addc_co_u32_e32 v13, vcc, 0, v33, vcc
	v_mov_b32_e32 v36, v162
	v_add_co_u32_e32 v14, vcc, s47, v30
	v_readlane_b32 s84, v247, 34
	s_nop 0
	v_addc_co_u32_e32 v15, vcc, 0, v31, vcc
	v_mov_b32_e32 v53, v175
	v_mov_b32_e32 v112, v184
	v_mov_b32_e32 v113, v185
	v_mov_b32_e32 v37, v163
	v_mov_b32_e32 v38, v164
	v_mov_b32_e32 v54, v176
	v_mov_b32_e32 v100, v182
	v_mov_b32_e32 v98, v180
	v_mov_b32_e32 v55, v177
	v_mov_b32_e32 v101, v183
	v_mov_b32_e32 v60, v178
	v_mov_b32_e32 v97, v179
	v_mov_b32_e32 v22, v148
	s_add_i32 s69, s48, s30
	s_cmpk_lt_i32 s69, 0x1000
	s_cbranch_scc0 .Lmy_p6_nopf
	v_mov_b32_e32 v146, v20
	v_mov_b32_e32 v149, v23
	s_bfe_u32 s67, s69, 0x30007
	s_lshl_b32 s68, s67, 7
	v_readlane_b32 s76, v247, 26
	v_or_b32_e32 v126, s68, v146
	v_readlane_b32 s82, v247, 32
	v_readlane_b32 s83, v247, 33
	v_lshlrev_b32_e32 v148, 2, v126
	s_mov_b64 s[54:55], s[82:83]
	v_lshl_add_u64 v[126:127], s[54:55], 0, v[148:149]
	s_ashr_i32 s62, s69, 10
	v_add_co_u32_e32 v126, vcc, 0x1000, v126
	s_and_b32 s66, s69, 0x7f
	s_nop 0
	v_addc_co_u32_e32 v127, vcc, 0, v127, vcc
	s_ashr_i32 s63, s62, 31
	global_load_dwordx2 v[126:127], v[126:127], off
	s_nop 0
	global_load_dwordx2 v[128:129], v148, s[82:83]
	s_lshl_b64 s[64:65], s[62:63], 23
	v_lshl_add_u32 v148, s66, 16, v94
	v_lshl_add_u64 v[130:131], s[64:65], 0, v[148:149]
	v_or_b32_e32 v130, s68, v130
	v_or_b32_e32 v130, v130, v146
	v_lshlrev_b64 v[152:153], 1, v[130:131]
	v_lshl_add_u64 v[160:161], s[34:35], 0, v[152:153]
	v_add_co_u32_e32 v130, vcc, s33, v160
	v_lshl_add_u64 v[158:159], s[36:37], 0, v[152:153]
	s_nop 0
	v_addc_co_u32_e32 v131, vcc, 0, v161, vcc
	v_add_co_u32_e32 v132, vcc, s33, v158
	v_lshl_add_u64 v[156:157], s[38:39], 0, v[152:153]
	s_nop 0
	v_addc_co_u32_e32 v133, vcc, 0, v159, vcc
	global_load_dword v142, v[158:159], off
	global_load_dword v172, v[156:157], off offset:2048
	global_load_dword v181, v[130:131], off offset:2048
	global_load_dword v143, v[132:133], off offset:2048
	global_load_dword v144, v[158:159], off offset:2048
	v_add_co_u32_e32 v130, vcc, s46, v158
	v_readlane_b32 s77, v247, 27
	s_nop 0
	v_addc_co_u32_e32 v131, vcc, 0, v159, vcc
	v_add_co_u32_e32 v132, vcc, s46, v160
	global_load_dword v145, v[130:131], off offset:-4096
	global_load_dword v154, v[130:131], off
	v_addc_co_u32_e32 v133, vcc, 0, v161, vcc
	v_add_co_u32_e32 v134, vcc, s33, v156
	v_readlane_b32 s78, v247, 28
	s_nop 0
	v_addc_co_u32_e32 v135, vcc, 0, v157, vcc
	v_add_co_u32_e32 v136, vcc, s46, v156
	v_readlane_b32 s79, v247, 29
	s_nop 0
	v_addc_co_u32_e32 v137, vcc, 0, v157, vcc
	global_load_dword v173, v[136:137], off
	global_load_dword v174, v[136:137], off offset:2048
	global_load_dword v155, v[130:131], off offset:2048
	v_add_co_u32_e32 v130, vcc, s47, v160
	v_readlane_b32 s80, v247, 30
	s_nop 0
	v_addc_co_u32_e32 v131, vcc, 0, v161, vcc
	v_add_co_u32_e32 v138, vcc, s47, v158
	v_readlane_b32 s81, v247, 31
	s_nop 0
	v_addc_co_u32_e32 v139, vcc, 0, v159, vcc
	global_load_dword v162, v[138:139], off
	v_add_co_u32_e32 v140, vcc, s47, v156
	v_readlane_b32 s84, v247, 34
	s_nop 0
	v_addc_co_u32_e32 v141, vcc, 0, v157, vcc
	global_load_dword v175, v[156:157], off
	global_load_dword v184, v[160:161], off
	global_load_dword v185, v[160:161], off offset:2048
	global_load_dword v163, v[140:141], off offset:2048
	global_load_dword v164, v[138:139], off offset:2048
	global_load_dword v176, v[136:137], off offset:-4096
	global_load_dword v182, v[132:133], off
	global_load_dword v180, v[132:133], off offset:2048
	global_load_dword v177, v[140:141], off
	global_load_dword v183, v[132:133], off offset:-4096
	global_load_dword v178, v[134:135], off offset:2048
	global_load_dword v179, v[130:131], off
	global_load_dword v148, v[130:131], off offset:2048
.Lmy_p6_nopf:
	v_readlane_b32 s85, v247, 35
	v_readlane_b32 s86, v247, 36
	v_readlane_b32 s87, v247, 37
	v_readlane_b32 s88, v247, 38
	v_readlane_b32 s89, v247, 39
	v_readlane_b32 s90, v247, 40
	v_readlane_b32 s91, v247, 41
	v_sub_f32_e32 v0, v0, v2
	v_sub_f32_e32 v1, v1, v3
	v_mul_f32_e32 v0, 0x3fb8aa3b, v0
	v_mul_f32_e32 v1, 0x3fb8aa3b, v1
	v_exp_f32_e32 v0, v0
	v_exp_f32_e32 v1, v1
	v_lshlrev_b32_e32 v2, 16, v16
	v_pk_add_f32 v[0:1], v[0:1], 1.0 op_sel_hi:[1,0]
	v_lshlrev_b32_e32 v4, 16, v18
	v_and_b32_e32 v5, 0xffff0000, v18
	v_div_scale_f32 v18, s[44:45], v1, v1, 1.0
	v_and_b32_e32 v3, 0xffff0000, v16
	v_mul_f32_e32 v2, 0xbfb8aa3b, v2
	v_mul_f32_e32 v3, 0xbfb8aa3b, v3
	v_lshlrev_b32_e32 v6, 16, v19
	v_and_b32_e32 v7, 0xffff0000, v19
	v_rcp_f32_e32 v19, v18
	v_lshlrev_b32_e32 v10, 16, v28
	v_and_b32_e32 v11, 0xffff0000, v28
	v_mul_f32_e32 v4, 0xbfb8aa3b, v4
	v_fma_f32 v28, -v18, v19, 1.0
	v_fmac_f32_e32 v19, v28, v19
	v_div_scale_f32 v28, vcc, 1.0, v1, 1.0
	v_mul_f32_e32 v5, 0xbfb8aa3b, v5
	v_exp_f32_e32 v2, v2
	v_exp_f32_e32 v3, v3
	v_exp_f32_e32 v4, v4
	v_lshlrev_b32_e32 v12, 16, v29
	v_and_b32_e32 v13, 0xffff0000, v29
	v_mul_f32_e32 v29, v28, v19
	v_exp_f32_e32 v5, v5
	v_mul_f32_e32 v6, 0xbfb8aa3b, v6
	v_mul_f32_e32 v7, 0xbfb8aa3b, v7
	v_lshlrev_b32_e32 v8, 16, v17
	v_and_b32_e32 v9, 0xffff0000, v17
	v_exp_f32_e32 v6, v6
	v_exp_f32_e32 v7, v7
	v_mul_f32_e32 v8, 0xbfb8aa3b, v8
	v_lshlrev_b32_e32 v14, 16, v36
	v_and_b32_e32 v15, 0xffff0000, v36
	v_fma_f32 v36, -v18, v29, v28
	v_fmac_f32_e32 v29, v36, v19
	v_fma_f32 v18, -v18, v29, v28
	v_div_scale_f32 v28, s[44:45], v0, v0, 1.0
	v_rcp_f32_e32 v36, v28
	v_div_fmas_f32 v18, v18, v19, v29
	v_div_fixup_f32 v1, v18, v1, 1.0
	v_mul_f32_e32 v9, 0xbfb8aa3b, v9
	v_fma_f32 v18, -v28, v36, 1.0
	v_fmac_f32_e32 v36, v18, v36
	v_div_scale_f32 v18, vcc, 1.0, v0, 1.0
	v_exp_f32_e32 v8, v8
	v_exp_f32_e32 v9, v9
	v_mul_f32_e32 v10, 0xbfb8aa3b, v10
	v_mul_f32_e32 v11, 0xbfb8aa3b, v11
	v_mul_f32_e32 v19, v18, v36
	v_exp_f32_e32 v10, v10
	v_exp_f32_e32 v11, v11
	v_mul_f32_e32 v12, 0xbfb8aa3b, v12
	v_mul_f32_e32 v13, 0xbfb8aa3b, v13
	v_fma_f32 v29, -v28, v19, v18
	v_add_f32_e32 v2, 1.0, v2
	v_add_f32_e32 v3, 1.0, v3
	v_add_f32_e32 v4, 1.0, v4
	v_add_f32_e32 v5, 1.0, v5
	v_exp_f32_e32 v12, v12
	v_exp_f32_e32 v13, v13
	v_mul_f32_e32 v14, 0xbfb8aa3b, v14
	v_mul_f32_e32 v15, 0xbfb8aa3b, v15
	v_lshlrev_b32_e32 v16, 16, v38
	v_and_b32_e32 v17, 0xffff0000, v38
	v_fmac_f32_e32 v19, v29, v36
	v_rcp_f32_e32 v2, v2
	v_rcp_f32_e32 v3, v3
	v_rcp_f32_e32 v4, v4
	v_rcp_f32_e32 v5, v5
	v_add_f32_e32 v6, 1.0, v6
	v_add_f32_e32 v7, 1.0, v7
	v_exp_f32_e32 v14, v14
	v_exp_f32_e32 v15, v15
	v_mul_f32_e32 v16, 0xbfb8aa3b, v16
	v_mul_f32_e32 v17, 0xbfb8aa3b, v17
	v_fma_f32 v18, -v28, v19, v18
	v_rcp_f32_e32 v6, v6
	v_rcp_f32_e32 v7, v7
	v_add_f32_e32 v8, 1.0, v8
	v_add_f32_e32 v9, 1.0, v9
	v_exp_f32_e32 v16, v16
	v_exp_f32_e32 v17, v17
	v_div_fmas_f32 v18, v18, v36, v19
	v_rcp_f32_e32 v8, v8
	v_rcp_f32_e32 v9, v9
	v_add_f32_e32 v10, 1.0, v10
	v_add_f32_e32 v11, 1.0, v11
	v_div_fixup_f32 v0, v18, v0, 1.0
	v_rcp_f32_e32 v10, v10
	v_rcp_f32_e32 v11, v11
	v_add_f32_e32 v12, 1.0, v12
	v_add_f32_e32 v13, 1.0, v13
	v_pk_add_f32 v[18:19], v[0:1], 1.0 op_sel_hi:[1,0] neg_lo:[1,0] neg_hi:[1,0]
	v_rcp_f32_e32 v12, v12
	v_rcp_f32_e32 v13, v13
	v_add_f32_e32 v14, 1.0, v14
	v_add_f32_e32 v15, 1.0, v15
	v_pk_fma_f32 v[86:87], v[18:19], v[2:3], v[0:1]
	v_pk_fma_f32 v[78:79], v[18:19], v[4:5], v[0:1]
	v_lshlrev_b32_e32 v2, 16, v37
	v_and_b32_e32 v3, 0xffff0000, v37
	v_lshlrev_b32_e32 v4, 16, v55
	v_and_b32_e32 v5, 0xffff0000, v55
	v_rcp_f32_e32 v14, v14
	v_rcp_f32_e32 v15, v15
	v_add_f32_e32 v16, 1.0, v16
	v_add_f32_e32 v17, 1.0, v17
	v_pk_fma_f32 v[64:65], v[18:19], v[6:7], v[0:1]
	v_mul_f32_e32 v2, 0xbfb8aa3b, v2
	v_mul_f32_e32 v3, 0xbfb8aa3b, v3
	v_mul_f32_e32 v4, 0xbfb8aa3b, v4
	v_mul_f32_e32 v5, 0xbfb8aa3b, v5
	v_lshlrev_b32_e32 v6, 16, v52
	v_and_b32_e32 v7, 0xffff0000, v52
	v_rcp_f32_e32 v16, v16
	v_rcp_f32_e32 v17, v17
	v_pk_fma_f32 v[56:57], v[18:19], v[8:9], v[0:1]
	v_exp_f32_e32 v2, v2
	v_exp_f32_e32 v3, v3
	v_exp_f32_e32 v4, v4
	v_exp_f32_e32 v5, v5
	v_mul_f32_e32 v6, 0xbfb8aa3b, v6
	v_mul_f32_e32 v7, 0xbfb8aa3b, v7
	v_lshlrev_b32_e32 v8, 16, v47
	v_and_b32_e32 v9, 0xffff0000, v47
	v_pk_fma_f32 v[48:49], v[18:19], v[10:11], v[0:1]
	v_exp_f32_e32 v6, v6
	v_exp_f32_e32 v7, v7
	v_mul_f32_e32 v8, 0xbfb8aa3b, v8
	v_mul_f32_e32 v9, 0xbfb8aa3b, v9
	v_lshlrev_b32_e32 v10, 16, v60
	v_and_b32_e32 v11, 0xffff0000, v60
	v_pk_fma_f32 v[42:43], v[18:19], v[12:13], v[0:1]
	v_exp_f32_e32 v8, v8
	v_exp_f32_e32 v9, v9
	v_mul_f32_e32 v10, 0xbfb8aa3b, v10
	v_mul_f32_e32 v11, 0xbfb8aa3b, v11
	v_lshlrev_b32_e32 v12, 16, v54
	v_and_b32_e32 v13, 0xffff0000, v54
	v_pk_fma_f32 v[38:39], v[18:19], v[14:15], v[0:1]
	v_exp_f32_e32 v10, v10
	v_exp_f32_e32 v11, v11
	v_mul_f32_e32 v12, 0xbfb8aa3b, v12
	v_mul_f32_e32 v13, 0xbfb8aa3b, v13
	v_lshlrev_b32_e32 v14, 16, v46
	v_and_b32_e32 v15, 0xffff0000, v46
	v_pk_fma_f32 v[28:29], v[18:19], v[16:17], v[0:1]
	v_add_f32_e32 v2, 1.0, v2
	v_add_f32_e32 v3, 1.0, v3
	v_add_f32_e32 v4, 1.0, v4
	v_add_f32_e32 v5, 1.0, v5
	v_exp_f32_e32 v12, v12
	v_exp_f32_e32 v13, v13
	v_mul_f32_e32 v14, 0xbfb8aa3b, v14
	v_mul_f32_e32 v15, 0xbfb8aa3b, v15
	v_lshlrev_b32_e32 v16, 16, v53
	v_and_b32_e32 v17, 0xffff0000, v53
	v_rcp_f32_e32 v2, v2
	v_rcp_f32_e32 v3, v3
	v_rcp_f32_e32 v4, v4
	v_rcp_f32_e32 v5, v5
	v_add_f32_e32 v6, 1.0, v6
	v_add_f32_e32 v7, 1.0, v7
	v_exp_f32_e32 v14, v14
	v_exp_f32_e32 v15, v15
	v_mul_f32_e32 v16, 0xbfb8aa3b, v16
	v_mul_f32_e32 v17, 0xbfb8aa3b, v17
	v_rcp_f32_e32 v6, v6
	v_rcp_f32_e32 v7, v7
	v_add_f32_e32 v8, 1.0, v8
	v_add_f32_e32 v9, 1.0, v9
	v_exp_f32_e32 v16, v16
	v_exp_f32_e32 v17, v17
	v_rcp_f32_e32 v8, v8
	v_rcp_f32_e32 v9, v9
	v_add_f32_e32 v10, 1.0, v10
	v_add_f32_e32 v11, 1.0, v11
	v_rcp_f32_e32 v10, v10
	v_rcp_f32_e32 v11, v11
	v_add_f32_e32 v12, 1.0, v12
	v_add_f32_e32 v13, 1.0, v13
	v_rcp_f32_e32 v12, v12
	v_rcp_f32_e32 v13, v13
	v_add_f32_e32 v14, 1.0, v14
	v_add_f32_e32 v15, 1.0, v15
	v_pk_fma_f32 v[46:47], v[18:19], v[2:3], v[0:1]
	v_pk_fma_f32 v[54:55], v[18:19], v[4:5], v[0:1]
	v_pk_mul_f32 v[82:83], v[86:87], v[78:79]
	v_rcp_f32_e32 v14, v14
	v_rcp_f32_e32 v15, v15
	v_add_f32_e32 v16, 1.0, v16
	v_add_f32_e32 v17, 1.0, v17
	v_pk_mul_f32 v[60:61], v[54:55], v[46:47]
	v_pk_fma_f32 v[62:63], v[18:19], v[6:7], v[0:1]
	v_pk_mul_f32 v[72:73], v[82:83], v[64:65]
	v_rcp_f32_e32 v16, v16
	v_rcp_f32_e32 v17, v17
	v_pk_mul_f32 v[76:77], v[62:63], v[60:61]
	v_pk_fma_f32 v[80:81], v[18:19], v[8:9], v[0:1]
	v_pk_mul_f32 v[58:59], v[72:73], v[56:57]
	v_pk_mul_f32 v[84:85], v[80:81], v[76:77]
	v_pk_fma_f32 v[88:89], v[18:19], v[10:11], v[0:1]
	v_pk_mul_f32 v[50:51], v[58:59], v[48:49]
	v_pk_mul_f32 v[90:91], v[88:89], v[84:85]
	v_pk_fma_f32 v[92:93], v[18:19], v[12:13], v[0:1]
	v_pk_mul_f32 v[44:45], v[50:51], v[42:43]
	v_pk_mul_f32 v[102:103], v[92:93], v[90:91]
	v_pk_fma_f32 v[104:105], v[18:19], v[14:15], v[0:1]
	v_pk_mul_f32 v[40:41], v[44:45], v[38:39]
	v_pk_mul_f32 v[106:107], v[104:105], v[102:103]
	v_pk_fma_f32 v[108:109], v[18:19], v[16:17], v[0:1]
	v_pk_mul_f32 v[36:37], v[40:41], v[28:29]
	v_pk_mul_f32 v[110:111], v[108:109], v[106:107]
	ds_write2st64_b64 v95, v[36:37], v[110:111] offset1:8
	s_waitcnt lgkmcnt(0)
	s_barrier
	ds_read2st64_b64 v[8:11], v21 offset1:1
	ds_read2st64_b64 v[12:15], v21 offset0:2 offset1:3
	ds_read2st64_b64 v[0:3], v21 offset0:9 offset1:10
	v_lshlrev_b32_e32 v118, 16, v112
	v_and_b32_e32 v112, 0xffff0000, v112
	s_waitcnt lgkmcnt(2)
	v_cndmask_b32_e64 v4, v9, 1.0, s[0:1]
	v_cndmask_b32_e64 v5, v8, 1.0, s[0:1]
	v_mul_f32_e32 v6, v5, v10
	v_mul_f32_e32 v7, v4, v11
	v_cndmask_b32_e64 v16, v4, v7, s[2:3]
	v_cndmask_b32_e64 v17, v5, v6, s[2:3]
	s_waitcnt lgkmcnt(1)
	v_mul_f32_e32 v52, v17, v12
	v_mul_f32_e32 v53, v16, v13
	v_cndmask_b32_e64 v16, v16, v53, s[4:5]
	v_cndmask_b32_e64 v17, v17, v52, s[4:5]
	v_pk_mul_f32 v[8:9], v[8:9], v[10:11]
	ds_read2st64_b64 v[4:7], v21 offset0:11 offset1:12
	v_mul_f32_e32 v52, v17, v14
	v_mul_f32_e32 v53, v16, v15
	v_pk_mul_f32 v[8:9], v[8:9], v[12:13]
	v_cndmask_b32_e64 v16, v16, v53, s[8:9]
	v_cndmask_b32_e64 v17, v17, v52, s[8:9]
	v_pk_mul_f32 v[52:53], v[8:9], v[14:15]
	ds_read2st64_b64 v[8:11], v21 offset0:4 offset1:5
	s_waitcnt lgkmcnt(2)
	v_cndmask_b32_e64 v18, 1.0, v1, s[0:1]
	v_cndmask_b32_e64 v19, 1.0, v0, s[0:1]
	v_mul_f32_e32 v19, v19, v2
	v_mul_f32_e32 v18, v18, v3
	v_cndmask_b32_e64 v18, 1.0, v18, s[6:7]
	v_cndmask_b32_e64 v19, 1.0, v19, s[6:7]
	s_waitcnt lgkmcnt(1)
	v_mul_f32_e32 v12, v19, v4
	v_mul_f32_e32 v13, v18, v5
	v_cndmask_b32_e64 v18, 1.0, v13, s[10:11]
	v_cndmask_b32_e64 v19, 1.0, v12, s[10:11]
	ds_read2st64_b64 v[12:15], v21 offset0:6 offset1:7
	s_waitcnt lgkmcnt(1)
	v_mul_f32_e32 v66, v17, v8
	v_mul_f32_e32 v67, v16, v9
	v_cndmask_b32_e64 v67, v16, v67, s[12:13]
	v_cndmask_b32_e64 v66, v17, v66, s[12:13]
	v_mul_f32_e32 v16, v19, v6
	v_mul_f32_e32 v17, v18, v7
	v_cndmask_b32_e64 v68, 1.0, v17, s[14:15]
	v_cndmask_b32_e64 v69, 1.0, v16, s[14:15]
	ds_read2st64_b64 v[16:19], v21 offset0:13 offset1:14
	v_mul_f32_e32 v70, v66, v10
	v_mul_f32_e32 v71, v67, v11
	v_cndmask_b32_e64 v67, v67, v71, s[16:17]
	v_cndmask_b32_e64 v66, v66, v70, s[16:17]
	ds_read_b64 v[70:71], v21 offset:7680
	s_waitcnt lgkmcnt(1)
	v_mul_f32_e32 v69, v69, v16
	v_mul_f32_e32 v68, v68, v17
	v_cndmask_b32_e64 v68, 1.0, v68, s[18:19]
	v_cndmask_b32_e64 v69, 1.0, v69, s[18:19]
	v_mul_f32_e32 v74, v66, v12
	v_mul_f32_e32 v75, v67, v13
	v_cndmask_b32_e64 v67, v67, v75, s[20:21]
	v_cndmask_b32_e64 v66, v66, v74, s[20:21]
	v_mul_f32_e32 v69, v69, v18
	v_mul_f32_e32 v68, v68, v19
	v_cndmask_b32_e64 v68, 1.0, v68, s[22:23]
	v_cndmask_b32_e64 v69, 1.0, v69, s[22:23]
	v_mul_f32_e32 v74, v66, v14
	v_mul_f32_e32 v75, v67, v15
	v_cndmask_b32_e64 v114, v67, v75, s[24:25]
	v_cndmask_b32_e64 v115, v66, v74, s[24:25]
	s_waitcnt lgkmcnt(0)
	v_mul_f32_e32 v66, v69, v70
	v_mul_f32_e32 v67, v68, v71
	v_cndmask_b32_e64 v116, 1.0, v67, s[26:27]
	v_cndmask_b32_e64 v117, 1.0, v66, s[26:27]
	v_pk_mul_f32 v[66:67], v[6:7], v[16:17]
	v_rcp_f32_e32 v74, v52
	v_pk_mul_f32 v[66:67], v[66:67], v[18:19]
	v_rcp_f32_e32 v75, v53
	v_pk_mul_f32 v[68:69], v[66:67], v[70:71]
	v_mul_f32_e32 v115, v74, v115
	v_rcp_f32_e32 v66, v68
	v_rcp_f32_e32 v67, v69
	v_mul_f32_e32 v114, v75, v114
	v_mul_f32_e32 v119, v86, v115
	v_mul_f32_e32 v117, v66, v117
	v_mul_f32_e32 v116, v67, v116
	v_mul_f32_e32 v120, v87, v114
	v_mul_f32_e32 v121, v110, v117
	v_mul_f32_e32 v122, v111, v116
	v_rcp_f32_e32 v110, v119
	v_rcp_f32_e32 v111, v120
	v_mul_f32_e32 v123, v119, v118
	v_mul_f32_e32 v124, v120, v112
	v_cvt_pk_bf16_f32 v119, v123, v124
	global_store_dword v[34:35], v119, off
	v_pk_add_f32 v[34:35], v[86:87], 1.0 op_sel_hi:[1,0] neg_lo:[1,0] neg_hi:[1,0]
	v_and_b32_e32 v87, 0xffff0000, v113
	v_pk_mul_f32 v[34:35], v[34:35], v[110:111]
	v_pk_add_f32 v[28:29], v[28:29], 1.0 op_sel_hi:[1,0] neg_lo:[1,0] neg_hi:[1,0]
	v_cvt_pk_bf16_f32 v34, v34, v35
	global_store_dword v[32:33], v34, off
	v_mul_f32_e32 v32, v121, v118
	v_mul_f32_e32 v33, v122, v112
	v_cvt_pk_bf16_f32 v86, v32, v33
	v_rcp_f32_e32 v32, v121
	v_rcp_f32_e32 v33, v122
	v_lshl_add_u64 v[34:35], s[40:41], 0, v[26:27]
	global_store_dword v[34:35], v86, off
	v_pk_add_f32 v[34:35], v[108:109], 1.0 op_sel_hi:[1,0] neg_lo:[1,0] neg_hi:[1,0]
	v_lshlrev_b32_e32 v86, 16, v113
	v_pk_mul_f32 v[32:33], v[34:35], v[32:33]
	s_nop 0
	v_cvt_pk_bf16_f32 v32, v32, v33
	global_store_dword v[30:31], v32, off
	v_mul_f32_e32 v32, v82, v115
	v_mul_f32_e32 v33, v83, v114
	v_mul_f32_e32 v30, v32, v86
	v_mul_f32_e32 v31, v33, v87
	v_rcp_f32_e32 v32, v32
	v_rcp_f32_e32 v33, v33
	v_mul_f32_e32 v82, v106, v117
	v_cvt_pk_bf16_f32 v106, v30, v31
	v_or_b32_e32 v30, 0x800, v26
	v_mov_b32_e32 v31, v27
	v_lshl_add_u64 v[34:35], s[34:35], 0, v[30:31]
	global_store_dword v[34:35], v106, off
	v_pk_add_f32 v[34:35], v[78:79], 1.0 op_sel_hi:[1,0] neg_lo:[1,0] neg_hi:[1,0]
	v_mul_f32_e32 v83, v107, v116
	v_pk_mul_f32 v[32:33], v[34:35], v[32:33]
	v_and_b32_e32 v79, 0xffff0000, v101
	v_cvt_pk_bf16_f32 v34, v32, v33
	v_lshl_add_u64 v[32:33], s[36:37], 0, v[30:31]
	global_store_dword v[32:33], v34, off
	v_mul_f32_e32 v32, v82, v86
	v_mul_f32_e32 v33, v83, v87
	v_cvt_pk_bf16_f32 v78, v32, v33
	v_rcp_f32_e32 v32, v82
	v_rcp_f32_e32 v33, v83
	v_lshl_add_u64 v[34:35], s[40:41], 0, v[30:31]
	global_store_dword v[34:35], v78, off
	v_pk_add_f32 v[34:35], v[104:105], 1.0 op_sel_hi:[1,0] neg_lo:[1,0] neg_hi:[1,0]
	v_lshl_add_u64 v[30:31], s[38:39], 0, v[30:31]
	v_pk_mul_f32 v[32:33], v[34:35], v[32:33]
	v_lshlrev_b32_e32 v78, 16, v101
	v_cvt_pk_bf16_f32 v32, v32, v33
	global_store_dword v[30:31], v32, off
	v_mul_f32_e32 v32, v72, v115
	v_mul_f32_e32 v33, v73, v114
	v_mul_f32_e32 v30, v32, v78
	v_mul_f32_e32 v31, v33, v79
	v_rcp_f32_e32 v32, v32
	v_rcp_f32_e32 v33, v33
	v_cvt_pk_bf16_f32 v82, v30, v31
	v_or_b32_e32 v30, 0x1000, v26
	v_mov_b32_e32 v31, v27
	v_lshl_add_u64 v[34:35], s[34:35], 0, v[30:31]
	global_store_dword v[34:35], v82, off
	v_pk_add_f32 v[34:35], v[64:65], 1.0 op_sel_hi:[1,0] neg_lo:[1,0] neg_hi:[1,0]
	v_mul_f32_e32 v72, v102, v117
	v_pk_mul_f32 v[32:33], v[34:35], v[32:33]
	v_mul_f32_e32 v73, v103, v116
	v_cvt_pk_bf16_f32 v34, v32, v33
	v_lshl_add_u64 v[32:33], s[36:37], 0, v[30:31]
	global_store_dword v[32:33], v34, off
	v_mul_f32_e32 v32, v72, v78
	v_mul_f32_e32 v33, v73, v79
	v_cvt_pk_bf16_f32 v64, v32, v33
	v_rcp_f32_e32 v32, v72
	v_rcp_f32_e32 v33, v73
	v_lshl_add_u64 v[34:35], s[40:41], 0, v[30:31]
	global_store_dword v[34:35], v64, off
	v_pk_add_f32 v[34:35], v[92:93], 1.0 op_sel_hi:[1,0] neg_lo:[1,0] neg_hi:[1,0]
	v_lshl_add_u64 v[30:31], s[38:39], 0, v[30:31]
	v_pk_mul_f32 v[32:33], v[34:35], v[32:33]
	v_lshlrev_b32_e32 v64, 16, v99
	v_cvt_pk_bf16_f32 v32, v32, v33
	global_store_dword v[30:31], v32, off
	v_and_b32_e32 v65, 0xffff0000, v99
	v_mul_f32_e32 v32, v58, v115
	v_mul_f32_e32 v33, v59, v114
	v_mul_f32_e32 v30, v32, v64
	v_mul_f32_e32 v31, v33, v65
	v_rcp_f32_e32 v32, v32
	v_rcp_f32_e32 v33, v33
	v_cvt_pk_bf16_f32 v72, v30, v31
	v_or_b32_e32 v30, 0x1800, v26
	v_mov_b32_e32 v31, v27
	v_lshl_add_u64 v[34:35], s[34:35], 0, v[30:31]
	global_store_dword v[34:35], v72, off
	v_pk_add_f32 v[34:35], v[56:57], 1.0 op_sel_hi:[1,0] neg_lo:[1,0] neg_hi:[1,0]
	v_mul_f32_e32 v58, v90, v117
	v_pk_mul_f32 v[32:33], v[34:35], v[32:33]
	v_mul_f32_e32 v59, v91, v116
	v_cvt_pk_bf16_f32 v34, v32, v33
	v_lshl_add_u64 v[32:33], s[36:37], 0, v[30:31]
	global_store_dword v[32:33], v34, off
	v_mul_f32_e32 v32, v58, v64
	v_mul_f32_e32 v33, v59, v65
	v_cvt_pk_bf16_f32 v56, v32, v33
	v_rcp_f32_e32 v32, v58
	v_rcp_f32_e32 v33, v59
	v_lshl_add_u64 v[34:35], s[40:41], 0, v[30:31]
	global_store_dword v[34:35], v56, off
	v_pk_add_f32 v[34:35], v[88:89], 1.0 op_sel_hi:[1,0] neg_lo:[1,0] neg_hi:[1,0]
	v_lshl_add_u64 v[30:31], s[38:39], 0, v[30:31]
	v_pk_mul_f32 v[32:33], v[34:35], v[32:33]
	v_lshlrev_b32_e32 v56, 16, v100
	v_cvt_pk_bf16_f32 v32, v32, v33
	global_store_dword v[30:31], v32, off
	v_and_b32_e32 v57, 0xffff0000, v100
	v_mul_f32_e32 v32, v50, v115
	v_mul_f32_e32 v33, v51, v114
	v_mul_f32_e32 v30, v32, v56
	v_mul_f32_e32 v31, v33, v57
	v_rcp_f32_e32 v32, v32
	v_rcp_f32_e32 v33, v33
	v_cvt_pk_bf16_f32 v58, v30, v31
	v_or_b32_e32 v30, 0x2000, v26
	v_mov_b32_e32 v31, v27
	v_lshl_add_u64 v[34:35], s[34:35], 0, v[30:31]
	global_store_dword v[34:35], v58, off
	v_pk_add_f32 v[34:35], v[48:49], 1.0 op_sel_hi:[1,0] neg_lo:[1,0] neg_hi:[1,0]
	v_mul_f32_e32 v50, v84, v117
	v_pk_mul_f32 v[32:33], v[34:35], v[32:33]
	v_mul_f32_e32 v51, v85, v116
	v_cvt_pk_bf16_f32 v34, v32, v33
	v_lshl_add_u64 v[32:33], s[36:37], 0, v[30:31]
	global_store_dword v[32:33], v34, off
	v_mul_f32_e32 v32, v50, v56
	v_mul_f32_e32 v33, v51, v57
	v_cvt_pk_bf16_f32 v48, v32, v33
	v_rcp_f32_e32 v32, v50
	v_rcp_f32_e32 v33, v51
	v_lshl_add_u64 v[34:35], s[40:41], 0, v[30:31]
	global_store_dword v[34:35], v48, off
	v_pk_add_f32 v[34:35], v[80:81], 1.0 op_sel_hi:[1,0] neg_lo:[1,0] neg_hi:[1,0]
	v_lshl_add_u64 v[30:31], s[38:39], 0, v[30:31]
	v_pk_mul_f32 v[32:33], v[34:35], v[32:33]
	v_lshlrev_b32_e32 v48, 16, v98
	v_cvt_pk_bf16_f32 v32, v32, v33
	global_store_dword v[30:31], v32, off
	v_and_b32_e32 v49, 0xffff0000, v98
	v_mul_f32_e32 v32, v44, v115
	v_mul_f32_e32 v33, v45, v114
	v_mul_f32_e32 v30, v32, v48
	v_mul_f32_e32 v31, v33, v49
	v_rcp_f32_e32 v32, v32
	v_rcp_f32_e32 v33, v33
	v_cvt_pk_bf16_f32 v50, v30, v31
	v_or_b32_e32 v30, 0x2800, v26
	v_mov_b32_e32 v31, v27
	v_lshl_add_u64 v[34:35], s[34:35], 0, v[30:31]
	global_store_dword v[34:35], v50, off
	v_pk_add_f32 v[34:35], v[42:43], 1.0 op_sel_hi:[1,0] neg_lo:[1,0] neg_hi:[1,0]
	v_mul_f32_e32 v44, v76, v117
	v_pk_mul_f32 v[32:33], v[34:35], v[32:33]
	v_mul_f32_e32 v45, v77, v116
	v_cvt_pk_bf16_f32 v34, v32, v33
	v_lshl_add_u64 v[32:33], s[36:37], 0, v[30:31]
	global_store_dword v[32:33], v34, off
	v_mul_f32_e32 v32, v44, v48
	v_mul_f32_e32 v33, v45, v49
	v_cvt_pk_bf16_f32 v42, v32, v33
	v_rcp_f32_e32 v32, v44
	v_rcp_f32_e32 v33, v45
	v_lshl_add_u64 v[34:35], s[40:41], 0, v[30:31]
	global_store_dword v[34:35], v42, off
	v_pk_add_f32 v[34:35], v[62:63], 1.0 op_sel_hi:[1,0] neg_lo:[1,0] neg_hi:[1,0]
	v_lshl_add_u64 v[30:31], s[38:39], 0, v[30:31]
	v_pk_mul_f32 v[32:33], v[34:35], v[32:33]
	v_lshlrev_b32_e32 v42, 16, v97
	v_cvt_pk_bf16_f32 v32, v32, v33
	global_store_dword v[30:31], v32, off
	v_and_b32_e32 v43, 0xffff0000, v97
	v_mul_f32_e32 v32, v40, v115
	v_mul_f32_e32 v33, v41, v114
	v_mul_f32_e32 v30, v32, v42
	v_mul_f32_e32 v31, v33, v43
	v_rcp_f32_e32 v32, v32
	v_rcp_f32_e32 v33, v33
	v_cvt_pk_bf16_f32 v44, v30, v31
	v_or_b32_e32 v30, 0x3000, v26
	v_mov_b32_e32 v31, v27
	v_lshl_add_u64 v[34:35], s[34:35], 0, v[30:31]
	global_store_dword v[34:35], v44, off
	v_pk_add_f32 v[34:35], v[38:39], 1.0 op_sel_hi:[1,0] neg_lo:[1,0] neg_hi:[1,0]
	v_mul_f32_e32 v40, v60, v117
	v_pk_mul_f32 v[32:33], v[34:35], v[32:33]
	v_mul_f32_e32 v41, v61, v116
	v_cvt_pk_bf16_f32 v34, v32, v33
	v_lshl_add_u64 v[32:33], s[36:37], 0, v[30:31]
	global_store_dword v[32:33], v34, off
	v_mul_f32_e32 v32, v40, v42
	v_mul_f32_e32 v33, v41, v43
	v_cvt_pk_bf16_f32 v38, v32, v33
	v_rcp_f32_e32 v32, v40
	v_rcp_f32_e32 v33, v41
	v_lshl_add_u64 v[34:35], s[40:41], 0, v[30:31]
	global_store_dword v[34:35], v38, off
	v_pk_add_f32 v[34:35], v[54:55], 1.0 op_sel_hi:[1,0] neg_lo:[1,0] neg_hi:[1,0]
	v_lshl_add_u64 v[30:31], s[38:39], 0, v[30:31]
	v_pk_mul_f32 v[32:33], v[34:35], v[32:33]
	v_lshlrev_b32_e32 v34, 16, v22
	v_cvt_pk_bf16_f32 v32, v32, v33
	global_store_dword v[30:31], v32, off
	v_and_b32_e32 v22, 0xffff0000, v22
	v_mul_f32_e32 v30, v36, v115
	v_mul_f32_e32 v31, v37, v114
	v_mul_f32_e32 v32, v30, v34
	v_mul_f32_e32 v33, v31, v22
	v_rcp_f32_e32 v30, v30
	v_rcp_f32_e32 v31, v31
	v_or_b32_e32 v26, 0x3800, v26
	v_mul_f32_e32 v35, v46, v117
	v_mul_f32_e32 v36, v47, v116
	v_pk_mul_f32 v[28:29], v[28:29], v[30:31]
	v_mul_f32_e32 v22, v36, v22
	v_cvt_pk_bf16_f32 v30, v28, v29
	v_lshl_add_u64 v[28:29], s[36:37], 0, v[26:27]
	global_store_dword v[28:29], v30, off
	v_mul_f32_e32 v28, v35, v34
	v_cvt_pk_bf16_f32 v22, v28, v22
	v_rcp_f32_e32 v28, v35
	v_rcp_f32_e32 v29, v36
	v_lshl_add_u64 v[30:31], s[40:41], 0, v[26:27]
	global_store_dword v[30:31], v22, off
	v_pk_add_f32 v[30:31], v[46:47], 1.0 op_sel_hi:[1,0] neg_lo:[1,0] neg_hi:[1,0]
	v_cvt_pk_bf16_f32 v37, v32, v33
	v_pk_mul_f32 v[28:29], v[30:31], v[28:29]
	v_lshl_add_u64 v[32:33], s[34:35], 0, v[26:27]
	v_cvt_pk_bf16_f32 v22, v28, v29
	v_lshl_add_u64 v[26:27], s[38:39], 0, v[26:27]
	global_store_dword v[32:33], v37, off
	global_store_dword v[26:27], v22, off
	s_and_saveexec_b64 s[44:45], s[0:1]
	s_cbranch_execz .LBB0_551
	ds_read_b64 v[26:27], v21 offset:4096
	s_lshl_b32 s42, s42, 3
	v_pk_mul_f32 v[8:9], v[52:53], v[8:9]
	s_or_b32 s42, s42, s50
	v_pk_mul_f32 v[8:9], v[8:9], v[10:11]
	s_waitcnt lgkmcnt(0)
	v_pk_mul_f32 v[0:1], v[26:27], v[0:1]
	s_lshl_b32 s43, s42, 7
	v_pk_mul_f32 v[0:1], v[0:1], v[2:3]
	s_add_i32 s42, s42, 32
	v_pk_mul_f32 v[8:9], v[8:9], v[12:13]
	v_pk_mul_f32 v[0:1], v[0:1], v[4:5]
	s_or_b32 s50, s43, s49
	s_ashr_i32 s43, s42, 31
	v_pk_mul_f32 v[8:9], v[8:9], v[14:15]
	v_pk_mul_f32 v[0:1], v[0:1], v[6:7]
	s_lshl_b64 s[42:43], s[42:43], 7
	s_xor_b32 s49, s49, 0x7f
	v_pk_mul_f32 v[0:1], v[0:1], v[16:17]
	s_or_b32 s42, s42, s49
	v_mad_i64_i32 v[2:3], s[50:51], s50, v96, v[24:25]
	v_pk_mul_f32 v[4:5], v[74:75], v[8:9]
	v_pk_mul_f32 v[0:1], v[0:1], v[18:19]
	global_store_dwordx2 v[2:3], v[52:53], off
	global_store_dwordx2 v[2:3], v[8:9], off offset:512
	global_store_dwordx2 v[2:3], v[4:5], off offset:1024
	s_mul_i32 s49, s43, 0x600
	v_mad_u64_u32 v[2:3], s[42:43], s42, v96, v[24:25]
	v_pk_mul_f32 v[0:1], v[0:1], v[70:71]
	v_add_u32_e32 v3, s49, v3
	global_store_dwordx2 v[2:3], v[68:69], off
	global_store_dwordx2 v[2:3], v[0:1], off offset:512
	v_pk_mul_f32 v[0:1], v[0:1], v[66:67]
	global_store_dwordx2 v[2:3], v[0:1], off offset:1024
	s_branch .LBB0_551
